# lever 8 (LDS reads deeper in the MFMA shadow): mixer A PV section - V^T fragments requested two MFMAs ahead through two spare register quads, waits re-derived
# baseline (speedup 1.0000x reference)
; #define LAS __attribute__((address_space(3)))
; __device__ __forceinline__ s16x4 lds_tr(const LAS unsigned char* p) { return __builtin_bit_cast(s16x4, __builtin_amdgcn_ds_read_tr16_b64_v4i16((LAS v4i16_t*)p)); }
; __device__ __forceinline__ void attnA_unit(LAS unsigned char* lds, const Args& A, int unit) {
;     ...
;                 float mx = fmaxf(mxp[0], mxp[1]);
;                 mx = fmaxf(mx, __shfl_xor(mx, 32));
;                 float lsp[2] = {0.f, 0.f};
; #pragma unroll
;                 for (int kt = 0; kt < 5; ++kt)
; #pragma unroll
;                     for (int i = 0; i < 16; ++i) { const float p = __builtin_amdgcn_exp2f(S[kt][i] - mx); S[kt][i] = p; lsp[i & 1] += p; }
;                 float ls = lsp[0] + lsp[1];
;                 ls += __shfl_xor(ls, 32);
;                 f32x16 o0, o1;
; #pragma unroll
;                 for (int i = 0; i < 16; ++i) { o0[i] = 0.f; o1[i] = 0.f; }
;                 const LAS unsigned char* vr0 = vt_l + (rb + 4 * hh + ((lane & 15) >> 2)) * AST + 32 * ((lane >> 4) & 1) + 8 * (lane & 3);
; #pragma unroll
;                 for (int kt = 0; kt < 5; ++kt)
; #pragma unroll
;                     for (int ks = 0; ks < 2; ++ks) {
;                         const bf16x8 pf = pack_frag(S[kt], ks);
;                         const LAS unsigned char* vr = vr0 + (32 * kt + 16 * ks) * AST;
;                         const s16x4 a0 = lds_tr(vr), a1 = lds_tr(vr + 8 * AST), c0 = lds_tr(vr + 64), c1 = lds_tr(vr + 8 * AST + 64);
.LmixA_join:
	v_and_b32_e32 v2, 64, v217
	v_xor_b32_e32 v1, 32, v217
	v_add_u32_e32 v2, 64, v2
	v_cmp_lt_i32_e32 vcc, v1, v2
	v_lshlrev_b32_e32 v32, v206, v164
	s_nop 0
	v_cndmask_b32_e32 v1, v217, v1, vcc
	v_lshlrev_b32_e32 v238, 2, v1
	ds_bpermute_b32 v1, v238, v0
	s_waitcnt lgkmcnt(0)
	v_max_f32_e32 v1, v1, v1
	v_max_f32_e32 v229, v0, v1
	v_add_u32_e32 v253, v180, v163
	v_mad_u64_u32 v[246:247], s[22:23], v253, s88, v[152:153]
	v_add_u32_e32 v163, 0xe800, v246
	ds_read_b64_tr_b16 v[186:187], v246 offset:59392
	ds_read_b64_tr_b16 v[188:189], v246 offset:60544
	ds_read_b64_tr_b16 v[248:249], v246 offset:59456
	ds_read_b64_tr_b16 v[250:251], v246 offset:60608
	v_mul_f32_e32 v229, 0x3e38aa3b, v229
	v_mov_b32_e32 v252, 0x3e38aa3b
	v_fma_f32 v10, v76, v252, -v229
	v_exp_f32_e32 v172, v10
	v_fma_f32 v10, v77, v252, -v229
	v_exp_f32_e32 v173, v10
	v_fma_f32 v10, v78, v252, -v229
	v_exp_f32_e32 v174, v10
	v_fma_f32 v10, v79, v252, -v229
	v_exp_f32_e32 v175, v10
	v_fma_f32 v10, v48, v252, -v229
	v_fma_f32 v8, v72, v252, -v229
	v_exp_f32_e32 v72, v10
	v_fma_f32 v10, v49, v252, -v229
	v_exp_f32_e32 v166, v8
	v_fma_f32 v8, v73, v252, -v229
	v_exp_f32_e32 v73, v10
	v_fma_f32 v10, v50, v252, -v229
	v_exp_f32_e32 v167, v8
	v_fma_f32 v8, v74, v252, -v229
	v_exp_f32_e32 v74, v10
	v_fma_f32 v10, v51, v252, -v229
	v_exp_f32_e32 v75, v10
	v_fma_f32 v10, v52, v252, -v229
	v_exp_f32_e32 v76, v10
	v_fma_f32 v10, v53, v252, -v229
	v_exp_f32_e32 v77, v10
	v_fma_f32 v10, v54, v252, -v229
	v_exp_f32_e32 v78, v10
	v_fma_f32 v10, v55, v252, -v229
	v_exp_f32_e32 v79, v10
	v_fma_f32 v10, v56, v252, -v229
	v_exp_f32_e32 v62, v10
	v_fma_f32 v10, v57, v252, -v229
	v_exp_f32_e32 v63, v10
	v_fma_f32 v10, v58, v252, -v229
	v_fma_f32 v2, v66, v252, -v229
	v_exp_f32_e32 v66, v10
	v_fma_f32 v10, v59, v252, -v229
	v_fma_f32 v0, v64, v252, -v229
	v_fma_f32 v1, v65, v252, -v229
	v_fma_f32 v3, v67, v252, -v229
	v_exp_f32_e32 v67, v10
	v_fma_f32 v10, v60, v252, -v229
	v_exp_f32_e32 v0, v0
	v_exp_f32_e32 v1, v1
	v_fma_f32 v4, v68, v252, -v229
	v_exp_f32_e32 v68, v10
	v_fma_f32 v10, v61, v252, -v229
	v_exp_f32_e32 v2, v2
	v_exp_f32_e32 v3, v3
	v_fma_f32 v5, v69, v252, -v229
	v_exp_f32_e32 v69, v10
	v_fma_f32 v10, v169, v252, -v229
	v_exp_f32_e32 v4, v4
	v_exp_f32_e32 v5, v5
	v_fma_f32 v6, v70, v252, -v229
	v_fma_f32 v7, v71, v252, -v229
	v_exp_f32_e32 v70, v10
	v_fma_f32 v10, v208, v252, -v229
	v_exp_f32_e32 v6, v6
	v_exp_f32_e32 v7, v7
	v_exp_f32_e32 v170, v8
	v_fma_f32 v8, v168, v252, -v229
	v_exp_f32_e32 v71, v10
	v_fma_f32 v10, v209, v252, -v229
	v_exp_f32_e32 v171, v8
	v_pk_add_f32 v[8:9], v[0:1], 0 op_sel_hi:[1,0]
	v_exp_f32_e32 v54, v10
	v_fma_f32 v10, v33, v252, -v229
	v_pk_add_f32 v[8:9], v[2:3], v[8:9]
	v_exp_f32_e32 v55, v10
	v_fma_f32 v10, v34, v252, -v229
	v_pk_add_f32 v[8:9], v[4:5], v[8:9]
	v_exp_f32_e32 v58, v10
	v_fma_f32 v10, v35, v252, -v229
	v_pk_add_f32 v[8:9], v[6:7], v[8:9]
	v_exp_f32_e32 v59, v10
	v_fma_f32 v10, v36, v252, -v229
	v_pk_add_f32 v[8:9], v[166:167], v[8:9]
	v_exp_f32_e32 v60, v10
	v_fma_f32 v10, v37, v252, -v229
	v_pk_add_f32 v[8:9], v[170:171], v[8:9]
	v_exp_f32_e32 v61, v10
	v_fma_f32 v10, v38, v252, -v229
	v_pk_add_f32 v[8:9], v[172:173], v[8:9]
	v_exp_f32_e32 v64, v10
	v_fma_f32 v10, v39, v252, -v229
	v_pk_add_f32 v[8:9], v[174:175], v[8:9]
	v_exp_f32_e32 v65, v10
	v_fma_f32 v10, v40, v252, -v229
	v_pk_add_f32 v[8:9], v[72:73], v[8:9]
	v_exp_f32_e32 v48, v10
	v_fma_f32 v10, v41, v252, -v229
	v_pk_add_f32 v[8:9], v[74:75], v[8:9]
	v_exp_f32_e32 v49, v10
	v_fma_f32 v10, v42, v252, -v229
	v_pk_add_f32 v[8:9], v[76:77], v[8:9]
	v_exp_f32_e32 v50, v10
	v_fma_f32 v10, v43, v252, -v229
	v_pk_add_f32 v[8:9], v[78:79], v[8:9]
	v_exp_f32_e32 v51, v10
	v_fma_f32 v10, v44, v252, -v229
	v_pk_add_f32 v[8:9], v[62:63], v[8:9]
	v_exp_f32_e32 v52, v10
	v_fma_f32 v10, v45, v252, -v229
	v_pk_add_f32 v[8:9], v[66:67], v[8:9]
	v_exp_f32_e32 v53, v10
	v_fma_f32 v10, v46, v252, -v229
	v_pk_add_f32 v[8:9], v[68:69], v[8:9]
	v_exp_f32_e32 v56, v10
	v_fma_f32 v10, v47, v252, -v229
	v_pk_add_f32 v[8:9], v[70:71], v[8:9]
	v_exp_f32_e32 v57, v10
	v_fma_f32 v10, v16, v252, -v229
	v_pk_add_f32 v[8:9], v[54:55], v[8:9]
	v_exp_f32_e32 v38, v10
	v_fma_f32 v10, v17, v252, -v229
	v_exp_f32_e32 v39, v10
	v_fma_f32 v10, v18, v252, -v229
	v_pk_add_f32 v[8:9], v[58:59], v[8:9]
	v_exp_f32_e32 v40, v10
	v_fma_f32 v10, v19, v252, -v229
	v_pk_add_f32 v[8:9], v[60:61], v[8:9]
	v_exp_f32_e32 v41, v10
	v_fma_f32 v10, v20, v252, -v229
	v_pk_add_f32 v[8:9], v[64:65], v[8:9]
	v_exp_f32_e32 v42, v10
	v_fma_f32 v10, v21, v252, -v229
	v_pk_add_f32 v[8:9], v[48:49], v[8:9]
	v_exp_f32_e32 v43, v10
	v_fma_f32 v10, v22, v252, -v229
	v_pk_add_f32 v[8:9], v[50:51], v[8:9]
	v_exp_f32_e32 v44, v10
	v_fma_f32 v10, v23, v252, -v229
	v_pk_add_f32 v[8:9], v[52:53], v[8:9]
	v_exp_f32_e32 v45, v10
	v_pk_add_f32 v[8:9], v[56:57], v[8:9]
	v_fma_f32 v12, v27, v252, -v229
	v_pk_add_f32 v[8:9], v[38:39], v[8:9]
	v_cvt_pk_bf16_f32 v16, v0, v1
	v_pk_add_f32 v[8:9], v[40:41], v[8:9]
	v_cvt_pk_bf16_f32 v17, v2, v3
	v_pk_add_f32 v[8:9], v[42:43], v[8:9]
	v_cvt_pk_bf16_f32 v18, v4, v5
	v_pk_add_f32 v[46:47], v[44:45], v[8:9]
	v_fma_f32 v8, v24, v252, -v229
	v_exp_f32_e32 v34, v8
	v_fma_f32 v8, v25, v252, -v229
	v_exp_f32_e32 v35, v8
	v_fma_f32 v8, v26, v252, -v229
	v_exp_f32_e32 v36, v8
	v_cvt_pk_bf16_f32 v19, v6, v7
	v_exp_f32_e32 v37, v12
	v_fma_f32 v24, v28, v252, -v229
	s_waitcnt lgkmcnt(2)
	v_mfma_f32_32x32x16_bf16 v[0:15], v[186:189], v[16:19], 0
	ds_read_b64_tr_b16 v[186:187], v246 offset:61696
	ds_read_b64_tr_b16 v[188:189], v246 offset:62848
	v_exp_f32_e32 v164, v24
	v_fma_f32 v24, v29, v252, -v229
	v_exp_f32_e32 v165, v24
	v_fma_f32 v24, v30, v252, -v229
	v_exp_f32_e32 v168, v24
	v_cvt_pk_bf16_f32 v242, v166, v167
	s_waitcnt lgkmcnt(2)
; #define LAS __attribute__((address_space(3)))
; #define MFMA32(a, b, c) __builtin_amdgcn_mfma_f32_32x32x16_bf16((a), (b), (c), 0, 0, 0)
; __device__ __forceinline__ s16x4 lds_tr(const LAS unsigned char* p) { return __builtin_bit_cast(s16x4, __builtin_amdgcn_ds_read_tr16_b64_v4i16((LAS v4i16_t*)p)); }
; __device__ __forceinline__ void attnA_unit(LAS unsigned char* lds, const Args& A, int unit) {
;     ...
;                 const LAS unsigned char* vr0 = vt_l + (rb + 4 * hh + ((lane & 15) >> 2)) * AST + 32 * ((lane >> 4) & 1) + 8 * (lane & 3);
; #pragma unroll
;                 for (int kt = 0; kt < 5; ++kt)
; #pragma unroll
;                     for (int ks = 0; ks < 2; ++ks) {
;                         const bf16x8 pf = pack_frag(S[kt], ks);
;                         const LAS unsigned char* vr = vr0 + (32 * kt + 16 * ks) * AST;
;                         const s16x4 a0 = lds_tr(vr), a1 = lds_tr(vr + 8 * AST), c0 = lds_tr(vr + 64), c1 = lds_tr(vr + 8 * AST + 64);
;                         o0 = MFMA32(__builtin_shufflevector(a0, a1, 0, 1, 2, 3, 4, 5, 6, 7), pf, o0);
;                         o1 = MFMA32(__builtin_shufflevector(c0, c1, 0, 1, 2, 3, 4, 5, 6, 7), pf, o1);
;                     }
	v_mfma_f32_32x32x16_bf16 v[16:31], v[248:251], v[16:19], 0
	ds_read_b64_tr_b16 v[248:249], v246 offset:61760
	ds_read_b64_tr_b16 v[250:251], v246 offset:62912
	v_cvt_pk_bf16_f32 v243, v170, v171
	v_cvt_pk_bf16_f32 v244, v172, v173
	v_cvt_pk_bf16_f32 v245, v174, v175
	v_cvt_pk_bf16_f32 v48, v48, v49
	v_cvt_pk_bf16_f32 v49, v50, v51
	s_waitcnt lgkmcnt(2)
	v_mfma_f32_32x32x16_bf16 v[0:15], v[186:189], v[242:245], v[0:15]
	ds_read_b64_tr_b16 v[186:187], v246 offset:64000
	ds_read_b64_tr_b16 v[188:189], v246 offset:65152
	v_cvt_pk_bf16_f32 v50, v52, v53
	v_cvt_pk_bf16_f32 v51, v56, v57
	v_fma_f32 v33, v224, v252, -v229
	v_exp_f32_e32 v169, v33
	v_fma_f32 v33, v223, v252, -v229
	v_cvt_pk_bf16_f32 v38, v38, v39
	s_waitcnt lgkmcnt(2)
	v_mfma_f32_32x32x16_bf16 v[16:31], v[248:251], v[242:245], v[16:31]
	ds_read_b64_tr_b16 v[248:249], v246 offset:64064
	ds_read_b64_tr_b16 v[250:251], v246 offset:65216
	v_cvt_pk_bf16_f32 v170, v72, v73
	v_cvt_pk_bf16_f32 v171, v74, v75
	v_cvt_pk_bf16_f32 v172, v76, v77
	v_cvt_pk_bf16_f32 v173, v78, v79
	v_cvt_pk_bf16_f32 v78, v68, v69
	v_cvt_pk_bf16_f32 v79, v70, v71
	s_waitcnt lgkmcnt(2)
	v_mfma_f32_32x32x16_bf16 v[0:15], v[186:189], v[170:173], v[0:15]
	ds_read_b64_tr_b16 v[186:187], v163 offset:6912
	ds_read_b64_tr_b16 v[188:189], v163 offset:8064
	v_cvt_pk_bf16_f32 v39, v40, v41
	v_cvt_pk_bf16_f32 v40, v42, v43
	v_cvt_pk_bf16_f32 v41, v44, v45
	v_exp_f32_e32 v166, v33
	v_fma_f32 v33, v226, v252, -v229
	v_exp_f32_e32 v167, v33
	s_waitcnt lgkmcnt(2)
	v_mfma_f32_32x32x16_bf16 v[16:31], v[248:251], v[170:173], v[16:31]
	ds_read_b64_tr_b16 v[248:249], v163 offset:6976
	ds_read_b64_tr_b16 v[250:251], v163 offset:8128
	v_cvt_pk_bf16_f32 v76, v62, v63
	v_cvt_pk_bf16_f32 v77, v66, v67
	v_fma_f32 v33, v225, v252, -v229
	v_exp_f32_e32 v72, v33
	v_fma_f32 v33, v227, v252, -v229
	s_waitcnt lgkmcnt(2)
	v_mfma_f32_32x32x16_bf16 v[0:15], v[186:189], v[76:79], v[0:15]
	ds_read_b64_tr_b16 v[186:187], v163 offset:9216
	ds_read_b64_tr_b16 v[188:189], v163 offset:10368
	v_exp_f32_e32 v73, v33
	v_fma_f32 v33, v228, v252, -v229
	v_exp_f32_e32 v74, v33
	v_fma_f32 v33, v230, v252, -v229
	v_exp_f32_e32 v75, v33
	v_fma_f32 v33, v232, v252, -v229
	v_exp_f32_e32 v62, v33
	s_waitcnt lgkmcnt(2)
	v_mfma_f32_32x32x16_bf16 v[16:31], v[248:251], v[76:79], v[16:31]
	ds_read_b64_tr_b16 v[248:249], v163 offset:9280
	ds_read_b64_tr_b16 v[250:251], v163 offset:10432
	v_cvt_pk_bf16_f32 v66, v54, v55
	v_cvt_pk_bf16_f32 v67, v58, v59
	v_cvt_pk_bf16_f32 v68, v60, v61
	v_cvt_pk_bf16_f32 v69, v64, v65
	v_fma_f32 v33, v233, v252, -v229
	s_waitcnt lgkmcnt(2)
	v_mfma_f32_32x32x16_bf16 v[0:15], v[186:189], v[66:69], v[0:15]
	ds_read_b64_tr_b16 v[186:187], v163 offset:11520
	ds_read_b64_tr_b16 v[188:189], v163 offset:12672
	v_exp_f32_e32 v63, v33
	v_fma_f32 v33, v231, v252, -v229
	v_exp_f32_e32 v54, v33
	v_fma_f32 v33, v234, v252, -v229
	v_exp_f32_e32 v55, v33
	v_fma_f32 v33, v235, v252, -v229
	s_waitcnt lgkmcnt(2)
	v_mfma_f32_32x32x16_bf16 v[16:31], v[248:251], v[66:69], v[16:31]
	ds_read_b64_tr_b16 v[248:249], v163 offset:11584
	ds_read_b64_tr_b16 v[250:251], v163 offset:12736
	v_exp_f32_e32 v60, v33
	v_fma_f32 v33, v236, v252, -v229
	v_exp_f32_e32 v61, v33
	v_fma_f32 v33, v237, v252, -v229
	s_waitcnt lgkmcnt(2)
	v_mfma_f32_32x32x16_bf16 v[0:15], v[186:189], v[48:51], v[0:15]
	ds_read_b64_tr_b16 v[186:187], v163 offset:13824
	ds_read_b64_tr_b16 v[188:189], v163 offset:14976
	v_exp_f32_e32 v52, v33
	v_fma_f32 v33, v240, v252, -v229
	v_exp_f32_e32 v53, v33
	v_fma_f32 v33, v239, v252, -v229
	s_waitcnt lgkmcnt(2)
	v_mfma_f32_32x32x16_bf16 v[16:31], v[248:251], v[48:51], v[16:31]
	ds_read_b64_tr_b16 v[248:249], v163 offset:13888
	ds_read_b64_tr_b16 v[250:251], v163 offset:15040
	v_add_f32_e64 v56, v34, v46
	v_add_f32_e64 v57, v35, v47
	v_cvt_pk_bf16_f32 v34, v34, v35
	v_cvt_pk_bf16_f32 v35, v36, v37
	v_exp_f32_e32 v50, v33
	v_fma_f32 v33, v241, v252, -v229
	v_exp_f32_e32 v51, v33
	s_waitcnt lgkmcnt(2)
	v_mfma_f32_32x32x16_bf16 v[0:15], v[186:189], v[38:41], v[0:15]
	ds_read_b64_tr_b16 v[186:187], v163 offset:16128
	ds_read_b64_tr_b16 v[188:189], v163 offset:17280
	s_waitcnt lgkmcnt(2)
	v_mfma_f32_32x32x16_bf16 v[16:31], v[248:251], v[38:41], v[16:31]
	ds_read_b64_tr_b16 v[248:249], v163 offset:16192
	ds_read_b64_tr_b16 v[250:251], v163 offset:17344
	v_add_f32_e64 v42, v36, v56
	v_add_f32_e64 v43, v37, v57
	v_cvt_pk_bf16_f32 v36, v164, v165
	v_cvt_pk_bf16_f32 v37, v168, v169
	v_add_f32_e64 v42, v164, v42
	v_add_f32_e64 v43, v165, v43
	v_pk_add_f32 v[42:43], v[168:169], v[42:43]
	s_waitcnt lgkmcnt(2)
; #define LAS __attribute__((address_space(3)))
; #define MFMA32(a, b, c) __builtin_amdgcn_mfma_f32_32x32x16_bf16((a), (b), (c), 0, 0, 0)
; __device__ __forceinline__ unsigned cvtpk(float lo, float hi) { f32x2_t v = {lo, hi}; bf16x2_t b = __builtin_convertvector(v, bf16x2_t); return __builtin_bit_cast(unsigned, b); }
; __device__ __forceinline__ s16x4 lds_tr(const LAS unsigned char* p) { return __builtin_bit_cast(s16x4, __builtin_amdgcn_ds_read_tr16_b64_v4i16((LAS v4i16_t*)p)); }
; __device__ __forceinline__ void attnA_unit(LAS unsigned char* lds, const Args& A, int unit) {
;     ...
;                 const LAS unsigned char* vr0 = vt_l + (rb + 4 * hh + ((lane & 15) >> 2)) * AST + 32 * ((lane >> 4) & 1) + 8 * (lane & 3);
; #pragma unroll
;                 for (int kt = 0; kt < 5; ++kt)
; #pragma unroll
;                     for (int ks = 0; ks < 2; ++ks) {
;                         const bf16x8 pf = pack_frag(S[kt], ks);
;                         const LAS unsigned char* vr = vr0 + (32 * kt + 16 * ks) * AST;
;                         const s16x4 a0 = lds_tr(vr), a1 = lds_tr(vr + 8 * AST), c0 = lds_tr(vr + 64), c1 = lds_tr(vr + 8 * AST + 64);
;                         o0 = MFMA32(__builtin_shufflevector(a0, a1, 0, 1, 2, 3, 4, 5, 6, 7), pf, o0);
;                         o1 = MFMA32(__builtin_shufflevector(c0, c1, 0, 1, 2, 3, 4, 5, 6, 7), pf, o1);
;                     }
;                 const float inv = 1.0f / ls;
;                 bf16* orow = Qrow + 4 * hh;
; #pragma unroll
;                 for (int g4 = 0; g4 < 4; ++g4) {
;                     u32x2 w; w.x = cvtpk(o0[4 * g4] * inv, o0[4 * g4 + 1] * inv); w.y = cvtpk(o0[4 * g4 + 2] * inv, o0[4 * g4 + 3] * inv); *(u32x2*)(orow + 8 * g4) = w;
;                     u32x2 z; z.x = cvtpk(o1[4 * g4] * inv, o1[4 * g4 + 1] * inv); z.y = cvtpk(o1[4 * g4 + 2] * inv, o1[4 * g4 + 3] * inv); *(u32x2*)(orow + 32 + 8 * g4) = z;
;                 }
;                 if (hh == 0) LSE[(size_t)((g * 4 + b) * 8 + h) * 8192 + pbase + i0 + ql] = mx + __builtin_amdgcn_logf(ls);
	v_mfma_f32_32x32x16_bf16 v[0:15], v[186:189], v[34:37], v[0:15]
	ds_read_b64_tr_b16 v[186:187], v163 offset:18432
	ds_read_b64_tr_b16 v[188:189], v163 offset:19584
	v_add_f32_e64 v42, v166, v42
	v_add_f32_e64 v43, v167, v43
	v_add_f32_e64 v42, v72, v42
	v_add_f32_e64 v43, v73, v43
	v_add_f32_e64 v46, v74, v42
	v_add_f32_e64 v47, v75, v43
	v_pk_add_f32 v[46:47], v[62:63], v[46:47]
	s_waitcnt lgkmcnt(2)
	v_mfma_f32_32x32x16_bf16 v[16:31], v[248:251], v[34:37], v[16:31]
	ds_read_b64_tr_b16 v[248:249], v163 offset:18496
	ds_read_b64_tr_b16 v[250:251], v163 offset:19648
	v_cvt_pk_bf16_f32 v34, v166, v167
	v_cvt_pk_bf16_f32 v35, v72, v73
	v_cvt_pk_bf16_f32 v36, v74, v75
	v_cvt_pk_bf16_f32 v37, v62, v63
	s_waitcnt lgkmcnt(2)
	v_mfma_f32_32x32x16_bf16 v[0:15], v[186:189], v[34:37], v[0:15]
	ds_read_b64_tr_b16 v[186:187], v163 offset:20736
	ds_read_b64_tr_b16 v[188:189], v163 offset:21888
	v_add_f32_e64 v42, v54, v46
	v_add_f32_e64 v43, v55, v47
	v_add_f32_e64 v42, v60, v42
	v_add_f32_e64 v43, v61, v43
	v_add_f32_e64 v42, v52, v42
	v_add_f32_e64 v43, v53, v43
	v_pk_add_f32 v[42:43], v[50:51], v[42:43]
	s_waitcnt lgkmcnt(2)
	v_mfma_f32_32x32x16_bf16 v[16:31], v[248:251], v[34:37], v[16:31]
	ds_read_b64_tr_b16 v[248:249], v163 offset:20800
	ds_read_b64_tr_b16 v[250:251], v163 offset:21952
	v_add_f32_e32 v33, v42, v43
	ds_bpermute_b32 v34, v238, v33
	v_cvt_pk_bf16_f32 v36, v54, v55
	v_cvt_pk_bf16_f32 v37, v60, v61
	s_waitcnt lgkmcnt(0)
	v_add_f32_e32 v34, v33, v34
	v_div_scale_f32 v33, s[22:23], v34, v34, 1.0
	v_rcp_f32_e32 v35, v33
	v_cvt_pk_bf16_f32 v38, v52, v53
	v_cvt_pk_bf16_f32 v39, v50, v51
	v_add3_u32 v40, v162, v144, v32
	v_ashrrev_i32_e32 v41, 31, v40
	v_mfma_f32_32x32x16_bf16 v[0:15], v[186:189], v[36:39], v[0:15]
	v_lshlrev_b64 v[40:41], 7, v[40:41]
	v_mfma_f32_32x32x16_bf16 v[16:31], v[248:251], v[36:39], v[16:31]
	v_fma_f32 v36, -v33, v35, 1.0
	v_fmac_f32_e32 v35, v36, v35
	v_div_scale_f32 v36, vcc, 1.0, v34, 1.0
	v_mul_f32_e32 v37, v36, v35
	v_fma_f32 v38, -v33, v37, v36
	v_fmac_f32_e32 v37, v38, v35
	v_fma_f32 v33, -v33, v37, v36
	v_div_fmas_f32 v33, v33, v35, v37
	v_div_fixup_f32 v36, v33, v34, 1.0
	v_pk_mul_f32 v[0:1], v[36:37], v[0:1] op_sel_hi:[0,1]
	v_pk_mul_f32 v[2:3], v[36:37], v[2:3] op_sel_hi:[0,1]
	v_lshl_add_u64 v[38:39], v[160:161], 0, v[40:41]
	v_cvt_pk_bf16_f32 v0, v0, v1
	v_cvt_pk_bf16_f32 v1, v2, v3
	global_store_dwordx2 v[38:39], v[0:1], off
	v_pk_mul_f32 v[0:1], v[36:37], v[16:17] op_sel_hi:[0,1]
	v_pk_mul_f32 v[2:3], v[36:37], v[18:19] op_sel_hi:[0,1]
	v_cvt_pk_bf16_f32 v0, v0, v1
	v_cvt_pk_bf16_f32 v1, v2, v3
	global_store_dwordx2 v[38:39], v[0:1], off offset:64
	v_pk_mul_f32 v[0:1], v[36:37], v[4:5] op_sel_hi:[0,1]
	v_pk_mul_f32 v[2:3], v[36:37], v[6:7] op_sel_hi:[0,1]
	v_cvt_pk_bf16_f32 v0, v0, v1
	v_cvt_pk_bf16_f32 v1, v2, v3
	global_store_dwordx2 v[38:39], v[0:1], off offset:16
	v_pk_mul_f32 v[0:1], v[36:37], v[20:21] op_sel_hi:[0,1]
	v_pk_mul_f32 v[2:3], v[36:37], v[22:23] op_sel_hi:[0,1]
	v_cvt_pk_bf16_f32 v0, v0, v1
	v_cvt_pk_bf16_f32 v1, v2, v3
	global_store_dwordx2 v[38:39], v[0:1], off offset:80
	v_pk_mul_f32 v[0:1], v[36:37], v[8:9] op_sel_hi:[0,1]
	v_pk_mul_f32 v[2:3], v[36:37], v[10:11] op_sel_hi:[0,1]
	v_cvt_pk_bf16_f32 v0, v0, v1
	v_cvt_pk_bf16_f32 v1, v2, v3
	global_store_dwordx2 v[38:39], v[0:1], off offset:32
	v_pk_mul_f32 v[0:1], v[36:37], v[24:25] op_sel_hi:[0,1]
	v_pk_mul_f32 v[2:3], v[36:37], v[26:27] op_sel_hi:[0,1]
	v_cvt_pk_bf16_f32 v0, v0, v1
	v_cvt_pk_bf16_f32 v1, v2, v3
	global_store_dwordx2 v[38:39], v[0:1], off offset:96
	v_pk_mul_f32 v[0:1], v[36:37], v[12:13] op_sel_hi:[0,1]
	v_pk_mul_f32 v[2:3], v[36:37], v[14:15] op_sel_hi:[0,1]
	v_cvt_pk_bf16_f32 v0, v0, v1
	v_cvt_pk_bf16_f32 v1, v2, v3
	global_store_dwordx2 v[38:39], v[0:1], off offset:48
	v_pk_mul_f32 v[0:1], v[36:37], v[28:29] op_sel_hi:[0,1]
	v_pk_mul_f32 v[2:3], v[36:37], v[30:31] op_sel_hi:[0,1]
	v_cvt_pk_bf16_f32 v0, v0, v1
	v_cvt_pk_bf16_f32 v1, v2, v3
	global_store_dwordx2 v[38:39], v[0:1], off offset:112
	s_and_saveexec_b64 s[22:23], s[6:7]
	s_cbranch_execz .LBB0_303
	v_log_f32_e32 v2, v34
	v_ashrrev_i32_e32 v33, 31, v32
	v_lshl_add_u64 v[0:1], v[32:33], 2, s[80:81]
	v_ashrrev_i32_e32 v163, 31, v162
	v_lshl_add_u64 v[0:1], v[162:163], 2, v[0:1]
	v_lshl_add_u64 v[0:1], v[0:1], 0, v[184:185]
	v_add_f32_e32 v2, v229, v2
	global_store_dword v[0:1], v2, off
